# NA: runs of serialized rel-pos-bias LDS lookups issued together with counted waits (10 runs, 34 of 64 lookups per unit)
# speedup vs baseline: 1.0118x; 1.0064x over previous
; #define LAS __attribute__((address_space(3)))
; DI f32x4 mfma32(bf16x8 a, bf16x8 b, f32x4 c) { return __builtin_amdgcn_mfma_f32_16x16x32_bf16(a, b, c, 0, 0, 0); }
; DI void phase_na(const Ctx& c, LAS unsigned char* lds, int g, int l, const bf16* PROJ, bf16* MIX, int bid, int nb, int tid) {
;     ...
;         for (int t = 0; t < 16; ++t) { const int rr = t >> 1, hf = t & 1, kr = r0 + rr;
;             const int krw_ = (kr - rbase) * 64 + kb0 + 16 * hf + li; const LAS unsigned char* kb_ = Kimg + krw_ * 128;
;             const bf16x8 ka_ = *(const LAS bf16x8*)(kb_ + ((gq ^ (krw_ & 7)) << 4)), kb2_ = *(const LAS bf16x8*)(kb_ + (((4 + gq) ^ (krw_ & 7)) << 4));
;             f32x4 sv = {0.f, 0.f, 0.f, 0.f}; sv = mfma32(ka_, qf0, sv); sv = mfma32(kb2_, qf1, sv);
;             const int dr = kr - r + 7;
; #pragma unroll
;             for (int j = 0; j < 4; ++j) sc[t][j] = sv[j] + rpbs[dr * 32 + dcx[hf * 4 + j]]; }
.LBB0_211:
	s_add_i32 s18, s18, -4
	s_min_i32 s0, s18, s62
	v_add_u32_e32 v91, -4, v93
	v_min_i32_e32 v91, s62, v91
	s_cmp_gt_u32 s1, 1
	v_cmp_lt_i32_e32 vcc, 3, v93
	s_cselect_b32 s0, s0, 0
	s_nop 0
	v_cndmask_b32_e32 v157, 0, v91, vcc
	v_subrev_u32_e32 v91, s0, v157
	v_lshl_add_u32 v142, v91, 13, v111
	v_add_u32_e32 v146, v142, v108
	ds_read_b128 v[138:141], v146
	v_add_u32_e32 v147, v142, v109
	ds_read_b128 v[142:145], v147
	v_add_u32_e32 v154, 1, v157
	s_waitcnt vmcnt(1) lgkmcnt(1)
	v_mfma_f32_16x16x32_bf16 v[138:141], v[138:141], v[78:81], 0
	v_lshlrev_b32_e32 v91, 6, v91
	s_waitcnt vmcnt(0) lgkmcnt(0)
	v_mfma_f32_16x16x32_bf16 v[142:145], v[142:145], v[82:85], v[138:141]
	s_nop 4
	v_sub_u32_e32 v138, v157, v93
	v_lshl_add_u32 v150, v138, 7, s26
	v_add_u32_e32 v244, v150, v130
	v_add_u32_e32 v245, v150, v131
	v_add_u32_e32 v246, v150, v132
	v_add_u32_e32 v247, v150, v133
	ds_read_b32 v244, v244 offset:896
	ds_read_b32 v245, v245 offset:896
	ds_read_b32 v246, v246 offset:896
	ds_read_b32 v247, v247 offset:896
	s_waitcnt lgkmcnt(3)
	v_add_f32_e32 v141, v142, v244
	s_waitcnt lgkmcnt(2)
	v_add_f32_e32 v140, v143, v245
	s_waitcnt lgkmcnt(1)
	v_add_f32_e32 v139, v144, v246
	s_waitcnt lgkmcnt(0)
	v_add_f32_e32 v138, v145, v247
	ds_read_b128 v[142:145], v146 offset:2048
	ds_read_b128 v[146:149], v147 offset:2048
	s_waitcnt lgkmcnt(1)
	v_mfma_f32_16x16x32_bf16 v[142:145], v[142:145], v[78:81], 0
	s_waitcnt lgkmcnt(0)
	v_mfma_f32_16x16x32_bf16 v[142:145], v[146:149], v[82:85], v[142:145]
	v_add_u32_e32 v244, v150, v134
	v_add_u32_e32 v245, v150, v135
	v_add_u32_e32 v246, v150, v136
	v_add_u32_e32 v247, v150, v137
	ds_read_b32 v244, v244 offset:896
	ds_read_b32 v245, v245 offset:896
	ds_read_b32 v246, v246 offset:896
	ds_read_b32 v247, v247 offset:896
	s_waitcnt lgkmcnt(3)
	s_nop 4
	v_add_f32_e32 v142, v142, v244
	s_waitcnt lgkmcnt(2)
	v_add_f32_e32 v143, v143, v245
	s_waitcnt lgkmcnt(1)
	v_add_f32_e32 v144, v144, v246
	s_waitcnt lgkmcnt(0)
	v_add_f32_e32 v145, v145, v247
	v_subrev_u32_e32 v146, s0, v154
	v_lshl_add_u32 v150, v146, 13, v111
	v_add_u32_e32 v155, v150, v108
	ds_read_b128 v[146:149], v155
	v_add_u32_e32 v156, v150, v109
	ds_read_b128 v[150:153], v156
	s_waitcnt lgkmcnt(1)
	v_mfma_f32_16x16x32_bf16 v[146:149], v[146:149], v[78:81], 0
	s_waitcnt lgkmcnt(0)
	v_mfma_f32_16x16x32_bf16 v[150:153], v[150:153], v[82:85], v[146:149]
	s_nop 5
	v_sub_u32_e32 v146, v154, v93
	v_lshl_add_u32 v154, v146, 7, s26
	v_add_u32_e32 v244, v154, v130
	v_add_u32_e32 v245, v154, v131
	v_add_u32_e32 v246, v154, v132
	v_add_u32_e32 v247, v154, v133
	ds_read_b32 v244, v244 offset:896
	ds_read_b32 v245, v245 offset:896
	ds_read_b32 v246, v246 offset:896
	ds_read_b32 v247, v247 offset:896
	s_waitcnt lgkmcnt(3)
	v_add_f32_e32 v149, v150, v244
	s_waitcnt lgkmcnt(2)
	v_add_f32_e32 v148, v151, v245
	s_waitcnt lgkmcnt(1)
	v_add_f32_e32 v147, v152, v246
	s_waitcnt lgkmcnt(0)
	v_add_f32_e32 v146, v153, v247
	ds_read_b128 v[150:153], v155 offset:2048
	ds_read_b128 v[164:167], v156 offset:2048
	s_waitcnt lgkmcnt(1)
	v_mfma_f32_16x16x32_bf16 v[150:153], v[150:153], v[78:81], 0
	v_add_u32_e32 v155, v154, v134
	ds_read_b32 v155, v155 offset:896
	s_waitcnt lgkmcnt(1)
	v_mfma_f32_16x16x32_bf16 v[150:153], v[164:167], v[82:85], v[150:153]
	s_waitcnt lgkmcnt(0)
	s_nop 6
	v_add_f32_e32 v150, v150, v155
	v_add_u32_e32 v155, v154, v135
	ds_read_b32 v155, v155 offset:896
	s_waitcnt lgkmcnt(0)
	v_add_f32_e32 v151, v151, v155
	v_add_u32_e32 v155, v154, v136
	v_add_u32_e32 v154, v154, v137
	ds_read_b32 v155, v155 offset:896
	ds_read_b32 v154, v154 offset:896
	s_waitcnt lgkmcnt(1)
	v_add_f32_e32 v152, v152, v155
	s_waitcnt lgkmcnt(0)
	v_add_f32_e32 v153, v153, v154
	v_add_u32_e32 v154, 2, v157
	v_subrev_u32_e32 v155, s0, v154
	v_lshl_add_u32 v155, v155, 13, v111
	v_add_u32_e32 v160, v155, v108
	ds_read_b128 v[164:167], v160
	v_add_u32_e32 v161, v155, v109
	ds_read_b128 v[168:171], v161
	v_sub_u32_e32 v154, v154, v93
	v_lshl_add_u32 v172, v154, 7, s26
	v_add_u32_e32 v154, v172, v130
	ds_read_b32 v154, v154 offset:896
	s_waitcnt lgkmcnt(2)
	v_mfma_f32_16x16x32_bf16 v[164:167], v[164:167], v[78:81], 0
	s_waitcnt lgkmcnt(1)
	v_mfma_f32_16x16x32_bf16 v[164:167], v[168:171], v[82:85], v[164:167]
	s_waitcnt lgkmcnt(0)
	s_nop 6
	v_add_f32_e32 v159, v164, v154
	v_add_u32_e32 v244, v172, v131
	v_add_u32_e32 v245, v172, v132
	v_add_u32_e32 v246, v172, v133
	ds_read_b32 v244, v244 offset:896
	ds_read_b32 v245, v245 offset:896
	ds_read_b32 v246, v246 offset:896
	s_waitcnt lgkmcnt(2)
	v_add_f32_e32 v156, v165, v244
	s_waitcnt lgkmcnt(1)
	v_add_f32_e32 v155, v166, v245
	s_waitcnt lgkmcnt(0)
	v_add_f32_e32 v154, v167, v246
	ds_read_b128 v[164:167], v160 offset:2048
	ds_read_b128 v[168:171], v161 offset:2048
	s_waitcnt lgkmcnt(1)
	v_mfma_f32_16x16x32_bf16 v[164:167], v[164:167], v[78:81], 0
	v_add_u32_e32 v160, v172, v134
	ds_read_b32 v160, v160 offset:896
	s_waitcnt lgkmcnt(1)
	v_mfma_f32_16x16x32_bf16 v[164:167], v[168:171], v[82:85], v[164:167]
	s_waitcnt lgkmcnt(0)
	s_nop 6
	v_add_f32_e32 v164, v164, v160
	v_add_u32_e32 v244, v172, v135
	v_add_u32_e32 v245, v172, v136
	v_add_u32_e32 v246, v172, v137
	ds_read_b32 v244, v244 offset:896
	ds_read_b32 v245, v245 offset:896
	ds_read_b32 v246, v246 offset:896
	s_waitcnt lgkmcnt(2)
	v_add_f32_e32 v165, v165, v244
	s_waitcnt lgkmcnt(1)
	v_add_f32_e32 v166, v166, v245
	s_waitcnt lgkmcnt(0)
	v_add_f32_e32 v167, v167, v246
	v_add_u32_e32 v160, 3, v157
	v_subrev_u32_e32 v161, s0, v160
	v_lshl_add_u32 v161, v161, 13, v111
	v_add_u32_e32 v176, v161, v108
	ds_read_b128 v[168:171], v176
	v_add_u32_e32 v161, v161, v109
	ds_read_b128 v[172:175], v161
	s_waitcnt lgkmcnt(1)
; #define LAS __attribute__((address_space(3)))
; DI f32x4 mfma32(bf16x8 a, bf16x8 b, f32x4 c) { return __builtin_amdgcn_mfma_f32_16x16x32_bf16(a, b, c, 0, 0, 0); }
; DI void phase_na(const Ctx& c, LAS unsigned char* lds, int g, int l, const bf16* PROJ, bf16* MIX, int bid, int nb, int tid) {
;     ...
;         for (int t = 0; t < 16; ++t) { const int rr = t >> 1, hf = t & 1, kr = r0 + rr;
;             const int krw_ = (kr - rbase) * 64 + kb0 + 16 * hf + li; const LAS unsigned char* kb_ = Kimg + krw_ * 128;
;             const bf16x8 ka_ = *(const LAS bf16x8*)(kb_ + ((gq ^ (krw_ & 7)) << 4)), kb2_ = *(const LAS bf16x8*)(kb_ + (((4 + gq) ^ (krw_ & 7)) << 4));
;             f32x4 sv = {0.f, 0.f, 0.f, 0.f}; sv = mfma32(ka_, qf0, sv); sv = mfma32(kb2_, qf1, sv);
;             const int dr = kr - r + 7;
; #pragma unroll
;             for (int j = 0; j < 4; ++j) sc[t][j] = sv[j] + rpbs[dr * 32 + dcx[hf * 4 + j]]; }
	v_mfma_f32_16x16x32_bf16 v[168:171], v[168:171], v[78:81], 0
	v_sub_u32_e32 v160, v160, v93
	v_lshl_add_u32 v160, v160, 7, s26
	s_waitcnt lgkmcnt(0)
	v_mfma_f32_16x16x32_bf16 v[172:175], v[172:175], v[82:85], v[168:171]
	s_nop 3
	v_add_u32_e32 v244, v160, v130
	v_add_u32_e32 v245, v160, v131
	v_add_u32_e32 v246, v160, v132
	v_add_u32_e32 v247, v160, v133
	ds_read_b32 v244, v244 offset:896
	ds_read_b32 v245, v245 offset:896
	ds_read_b32 v246, v246 offset:896
	ds_read_b32 v247, v247 offset:896
	s_waitcnt lgkmcnt(3)
	s_nop 0
	v_add_f32_e32 v171, v172, v244
	s_waitcnt lgkmcnt(2)
	v_add_f32_e32 v170, v173, v245
	s_waitcnt lgkmcnt(1)
	v_add_f32_e32 v169, v174, v246
	s_waitcnt lgkmcnt(0)
	v_add_f32_e32 v168, v175, v247
	ds_read_b128 v[172:175], v176 offset:2048
	ds_read_b128 v[176:179], v161 offset:2048
	s_waitcnt lgkmcnt(1)
	v_mfma_f32_16x16x32_bf16 v[172:175], v[172:175], v[78:81], 0
	v_add_u32_e32 v161, v160, v134
	ds_read_b32 v161, v161 offset:896
	s_waitcnt lgkmcnt(1)
	v_mfma_f32_16x16x32_bf16 v[172:175], v[176:179], v[82:85], v[172:175]
	s_waitcnt lgkmcnt(0)
	s_nop 6
	v_add_f32_e32 v172, v172, v161
	v_add_u32_e32 v161, v160, v135
	ds_read_b32 v161, v161 offset:896
	s_waitcnt lgkmcnt(0)
	v_add_f32_e32 v173, v173, v161
	v_add_u32_e32 v161, v160, v136
	v_add_u32_e32 v160, v160, v137
	ds_read_b32 v161, v161 offset:896
	ds_read_b32 v160, v160 offset:896
	s_waitcnt lgkmcnt(1)
	v_add_f32_e32 v174, v174, v161
	s_waitcnt lgkmcnt(0)
	v_add_f32_e32 v176, v175, v160
	v_add_u32_e32 v160, 4, v157
	v_subrev_u32_e32 v161, s0, v160
	v_lshl_add_u32 v161, v161, 13, v111
	v_add_u32_e32 v175, v161, v108
	ds_read_b128 v[178:181], v175
	v_add_u32_e32 v161, v161, v109
	ds_read_b128 v[182:185], v161
	s_waitcnt lgkmcnt(1)
	v_mfma_f32_16x16x32_bf16 v[178:181], v[178:181], v[78:81], 0
	v_sub_u32_e32 v160, v160, v93
	v_lshl_add_u32 v160, v160, 7, s26
	v_add_u32_e32 v177, v160, v130
	ds_read_b32 v177, v177 offset:896
	s_waitcnt lgkmcnt(1)
	v_mfma_f32_16x16x32_bf16 v[182:185], v[182:185], v[82:85], v[178:181]
	s_waitcnt lgkmcnt(0)
	s_nop 6
	v_add_f32_e32 v182, v182, v177
	v_add_u32_e32 v244, v160, v131
	v_add_u32_e32 v245, v160, v132
	v_add_u32_e32 v246, v160, v133
	ds_read_b32 v244, v244 offset:896
	ds_read_b32 v245, v245 offset:896
	ds_read_b32 v246, v246 offset:896
	s_waitcnt lgkmcnt(2)
	v_add_f32_e32 v181, v183, v244
	s_waitcnt lgkmcnt(1)
	v_add_f32_e32 v180, v184, v245
	s_waitcnt lgkmcnt(0)
	v_add_f32_e32 v179, v185, v246
	ds_read_b128 v[184:187], v175 offset:2048
	ds_read_b128 v[188:191], v161 offset:2048
	s_waitcnt lgkmcnt(1)
	v_mfma_f32_16x16x32_bf16 v[184:187], v[184:187], v[78:81], 0
	v_add_u32_e32 v161, v160, v134
	ds_read_b32 v161, v161 offset:896
	s_waitcnt lgkmcnt(1)
	v_mfma_f32_16x16x32_bf16 v[184:187], v[188:191], v[82:85], v[184:187]
	s_waitcnt lgkmcnt(0)
	s_nop 6
	v_add_f32_e32 v191, v184, v161
	v_add_u32_e32 v161, v160, v135
	ds_read_b32 v161, v161 offset:896
	s_waitcnt lgkmcnt(0)
	v_add_f32_e32 v192, v185, v161
	v_add_u32_e32 v161, v160, v136
	v_add_u32_e32 v160, v160, v137
	ds_read_b32 v161, v161 offset:896
	ds_read_b32 v160, v160 offset:896
	s_waitcnt lgkmcnt(1)
	v_add_f32_e32 v193, v186, v161
	s_waitcnt lgkmcnt(0)
	v_add_f32_e32 v194, v187, v160
	v_add_u32_e32 v160, 5, v157
	v_subrev_u32_e32 v161, s0, v160
	v_lshl_add_u32 v161, v161, 13, v111
	v_add_u32_e32 v175, v161, v108
	ds_read_b128 v[184:187], v175
	v_add_u32_e32 v161, v161, v109
	ds_read_b128 v[196:199], v161
	s_waitcnt lgkmcnt(1)
	v_mfma_f32_16x16x32_bf16 v[184:187], v[184:187], v[78:81], 0
	v_sub_u32_e32 v160, v160, v93
	v_lshl_add_u32 v160, v160, 7, s26
	v_add_u32_e32 v177, v160, v130
	ds_read_b32 v177, v177 offset:896
	s_waitcnt lgkmcnt(1)
	v_mfma_f32_16x16x32_bf16 v[184:187], v[196:199], v[82:85], v[184:187]
	s_waitcnt lgkmcnt(0)
	s_nop 6
	v_add_f32_e32 v204, v184, v177
	v_add_u32_e32 v244, v160, v131
	v_add_u32_e32 v245, v160, v132
	v_add_u32_e32 v246, v160, v133
	ds_read_b32 v244, v244 offset:896
	ds_read_b32 v245, v245 offset:896
	ds_read_b32 v246, v246 offset:896
	s_waitcnt lgkmcnt(2)
	v_add_f32_e32 v203, v185, v244
	s_waitcnt lgkmcnt(1)
	v_add_f32_e32 v201, v186, v245
	s_waitcnt lgkmcnt(0)
	v_add_f32_e32 v200, v187, v246
	ds_read_b128 v[184:187], v175 offset:2048
	ds_read_b128 v[196:199], v161 offset:2048
	s_waitcnt lgkmcnt(1)
	v_mfma_f32_16x16x32_bf16 v[184:187], v[184:187], v[78:81], 0
	v_add_u32_e32 v161, v160, v134
	ds_read_b32 v161, v161 offset:896
	s_waitcnt lgkmcnt(1)
	v_mfma_f32_16x16x32_bf16 v[184:187], v[196:199], v[82:85], v[184:187]
	s_waitcnt lgkmcnt(0)
	s_nop 6
	v_add_f32_e32 v213, v184, v161
	v_add_u32_e32 v161, v160, v135
	ds_read_b32 v161, v161 offset:896
	s_waitcnt lgkmcnt(0)
	v_add_f32_e32 v219, v185, v161
	v_add_u32_e32 v161, v160, v136
	v_add_u32_e32 v160, v160, v137
	ds_read_b32 v161, v161 offset:896
	ds_read_b32 v160, v160 offset:896
	s_waitcnt lgkmcnt(1)
	v_add_f32_e32 v220, v186, v161
	s_waitcnt lgkmcnt(0)
	v_add_f32_e32 v222, v187, v160
	v_add_u32_e32 v160, 6, v157
	v_subrev_u32_e32 v161, s0, v160
	v_lshl_add_u32 v161, v161, 13, v111
	v_add_u32_e32 v175, v161, v108
	ds_read_b128 v[184:187], v175
	v_add_u32_e32 v161, v161, v109
	ds_read_b128 v[196:199], v161
	s_waitcnt lgkmcnt(1)
	v_mfma_f32_16x16x32_bf16 v[184:187], v[184:187], v[78:81], 0
	v_sub_u32_e32 v160, v160, v93
	v_lshl_add_u32 v160, v160, 7, s26
	v_add_u32_e32 v177, v160, v130
	ds_read_b32 v177, v177 offset:896
	s_waitcnt lgkmcnt(1)
	v_mfma_f32_16x16x32_bf16 v[184:187], v[196:199], v[82:85], v[184:187]
	v_add_u32_e32 v157, 7, v157
	v_sub_u32_e32 v93, v157, v93
	s_waitcnt lgkmcnt(0)
; #define LAS __attribute__((address_space(3)))
; DI f32x4 mfma32(bf16x8 a, bf16x8 b, f32x4 c) { return __builtin_amdgcn_mfma_f32_16x16x32_bf16(a, b, c, 0, 0, 0); }
; DI void phase_na(const Ctx& c, LAS unsigned char* lds, int g, int l, const bf16* PROJ, bf16* MIX, int bid, int nb, int tid) {
;     ...
;         for (int t = 0; t < 16; ++t) { const int rr = t >> 1, hf = t & 1, kr = r0 + rr;
;             const int krw_ = (kr - rbase) * 64 + kb0 + 16 * hf + li; const LAS unsigned char* kb_ = Kimg + krw_ * 128;
;             const bf16x8 ka_ = *(const LAS bf16x8*)(kb_ + ((gq ^ (krw_ & 7)) << 4)), kb2_ = *(const LAS bf16x8*)(kb_ + (((4 + gq) ^ (krw_ & 7)) << 4));
;             f32x4 sv = {0.f, 0.f, 0.f, 0.f}; sv = mfma32(ka_, qf0, sv); sv = mfma32(kb2_, qf1, sv);
;             const int dr = kr - r + 7;
; #pragma unroll
;             for (int j = 0; j < 4; ++j) sc[t][j] = sv[j] + rpbs[dr * 32 + dcx[hf * 4 + j]]; }
;         float m = -3e38f;
; #pragma unroll
;         for (int t = 0; t < 16; ++t)
; #pragma unroll
;             for (int j = 0; j < 4; ++j) m = fmaxf(m, sc[t][j]);
;         m = fmaxf(m, __shfl_xor(m, 16)); m = fmaxf(m, __shfl_xor(m, 32));
;         float sum = 0.f;
; #pragma unroll
;         for (int t = 0; t < 16; ++t)
; #pragma unroll
;             for (int j = 0; j < 4; ++j) { const float p = __expf(sc[t][j] - m); sc[t][j] = p; sum += p; }
	s_nop 4
	v_add_f32_e32 v226, v184, v177
	v_add_u32_e32 v244, v160, v131
	v_add_u32_e32 v245, v160, v132
	v_add_u32_e32 v246, v160, v133
	ds_read_b32 v244, v244 offset:896
	ds_read_b32 v245, v245 offset:896
	ds_read_b32 v246, v246 offset:896
	s_waitcnt lgkmcnt(2)
	v_add_f32_e32 v225, v185, v244
	s_waitcnt lgkmcnt(1)
	v_add_f32_e32 v224, v186, v245
	s_waitcnt lgkmcnt(0)
	v_add_f32_e32 v223, v187, v246
	ds_read_b128 v[184:187], v175 offset:2048
	ds_read_b128 v[196:199], v161 offset:2048
	s_waitcnt lgkmcnt(1)
	v_mfma_f32_16x16x32_bf16 v[184:187], v[184:187], v[78:81], 0
	v_add_u32_e32 v161, v160, v134
	ds_read_b32 v161, v161 offset:896
	s_waitcnt lgkmcnt(1)
	v_mfma_f32_16x16x32_bf16 v[184:187], v[196:199], v[82:85], v[184:187]
	s_waitcnt lgkmcnt(0)
	s_nop 6
	v_add_f32_e32 v227, v184, v161
	v_add_u32_e32 v161, v160, v135
	ds_read_b32 v161, v161 offset:896
	s_waitcnt lgkmcnt(0)
	v_add_f32_e32 v228, v185, v161
	v_add_u32_e32 v161, v160, v136
	v_add_u32_e32 v160, v160, v137
	ds_read_b32 v161, v161 offset:896
	ds_read_b32 v160, v160 offset:896
	s_waitcnt lgkmcnt(1)
	v_add_f32_e32 v229, v186, v161
	s_waitcnt lgkmcnt(0)
	v_add_f32_e32 v230, v187, v160
	v_subrev_u32_e32 v160, s0, v157
	v_lshl_add_u32 v160, v160, 13, v111
	v_add_u32_e32 v161, v160, v108
	ds_read_b128 v[184:187], v161
	v_add_u32_e32 v160, v160, v109
	ds_read_b128 v[196:199], v160
	s_waitcnt lgkmcnt(1)
	v_mfma_f32_16x16x32_bf16 v[184:187], v[184:187], v[78:81], 0
	v_lshl_add_u32 v157, v93, 7, s26
	v_add_u32_e32 v93, v157, v130
	ds_read_b32 v93, v93 offset:896
	s_waitcnt lgkmcnt(1)
	v_mfma_f32_16x16x32_bf16 v[184:187], v[196:199], v[82:85], v[184:187]
	v_add_u32_e32 v175, v157, v133
	ds_read_b32 v175, v175 offset:896
	s_mov_b32 s0, 0xff61b1e6
	s_waitcnt lgkmcnt(1)
	s_nop 3
	v_add_f32_e32 v233, v184, v93
	v_add_u32_e32 v93, v157, v131
	ds_read_b32 v93, v93 offset:896
	s_waitcnt lgkmcnt(1)
	v_add_f32_e32 v231, v187, v175
	s_waitcnt lgkmcnt(0)
	v_add_f32_e32 v232, v185, v93
	v_add_u32_e32 v93, v157, v132
	ds_read_b32 v93, v93 offset:896
	s_waitcnt lgkmcnt(0)
	v_add_f32_e32 v93, v186, v93
	ds_read_b128 v[184:187], v161 offset:2048
	ds_read_b128 v[196:199], v160 offset:2048
	s_waitcnt lgkmcnt(1)
	v_mfma_f32_16x16x32_bf16 v[78:81], v[184:187], v[78:81], 0
	s_waitcnt lgkmcnt(0)
	v_mfma_f32_16x16x32_bf16 v[78:81], v[196:199], v[82:85], v[78:81]
	v_add_u32_e32 v244, v157, v134
	v_add_u32_e32 v245, v157, v135
	v_add_u32_e32 v246, v157, v136
	ds_read_b32 v244, v244 offset:896
	ds_read_b32 v245, v245 offset:896
	ds_read_b32 v246, v246 offset:896
	s_waitcnt lgkmcnt(2)
	s_nop 4
	v_add_f32_e32 v78, v78, v244
	s_waitcnt lgkmcnt(1)
	v_add_f32_e32 v79, v79, v245
	s_waitcnt lgkmcnt(0)
	v_add_f32_e32 v82, v80, v246
	v_add_u32_e32 v80, v157, v137
	ds_read_b32 v80, v80 offset:896
	s_waitcnt lgkmcnt(0)
	v_add_f32_e32 v83, v81, v80
	v_max3_f32 v80, v141, s0, v140
	v_max3_f32 v80, v80, v139, v138
	v_max3_f32 v80, v80, v142, v143
	v_max3_f32 v80, v80, v144, v145
	v_max3_f32 v80, v80, v149, v148
	v_max3_f32 v80, v80, v147, v146
	v_max3_f32 v80, v80, v150, v151
	v_max3_f32 v80, v80, v152, v153
	v_max3_f32 v80, v80, v159, v156
	v_max3_f32 v80, v80, v155, v154
	v_max3_f32 v80, v80, v164, v165
	v_max3_f32 v80, v80, v166, v167
	v_max3_f32 v80, v80, v171, v170
	v_max3_f32 v80, v80, v169, v168
	v_max3_f32 v80, v80, v172, v173
	v_max3_f32 v80, v80, v174, v176
	v_max3_f32 v80, v80, v182, v181
	v_max3_f32 v80, v80, v180, v179
	v_max3_f32 v80, v80, v191, v192
	v_max3_f32 v80, v80, v193, v194
	v_max3_f32 v80, v80, v204, v203
	v_max3_f32 v80, v80, v201, v200
	v_max3_f32 v80, v80, v213, v219
	v_max3_f32 v80, v80, v220, v222
	v_max3_f32 v80, v80, v226, v225
	v_max3_f32 v80, v80, v224, v223
	v_max3_f32 v80, v80, v227, v228
	v_max3_f32 v80, v80, v229, v230
	v_max3_f32 v80, v80, v233, v232
	v_max3_f32 v80, v80, v93, v231
	v_max3_f32 v80, v80, v78, v79
	v_max3_f32 v80, v80, v82, v83
	ds_bpermute_b32 v81, v105, v80
	s_waitcnt lgkmcnt(0)
	v_max_f32_e32 v81, v81, v81
	v_max_f32_e32 v80, v80, v81
	ds_bpermute_b32 v81, v106, v80
	s_waitcnt lgkmcnt(0)
	v_max_f32_e32 v81, v81, v81
	v_max_f32_e32 v160, v80, v81
	v_sub_f32_e32 v81, v140, v160
	v_mul_f32_e32 v81, 0x3fb8aa3b, v81
	v_exp_f32_e32 v212, v81
	v_sub_f32_e32 v81, v139, v160
	v_mul_f32_e32 v81, 0x3fb8aa3b, v81
	v_exp_f32_e32 v218, v81
	v_sub_f32_e32 v81, v138, v160
	v_mul_f32_e32 v81, 0x3fb8aa3b, v81
	v_exp_f32_e32 v221, v81
	v_sub_f32_e32 v81, v142, v160
	v_mul_f32_e32 v81, 0x3fb8aa3b, v81
	v_exp_f32_e32 v207, v81
	v_sub_f32_e32 v81, v143, v160
	v_mul_f32_e32 v81, 0x3fb8aa3b, v81
	v_exp_f32_e32 v208, v81
	v_sub_f32_e32 v81, v144, v160
	v_mul_f32_e32 v81, 0x3fb8aa3b, v81
	v_exp_f32_e32 v209, v81
	v_sub_f32_e32 v81, v145, v160
	v_mul_f32_e32 v81, 0x3fb8aa3b, v81
	v_exp_f32_e32 v211, v81
	v_sub_f32_e32 v81, v149, v160
	v_mul_f32_e32 v81, 0x3fb8aa3b, v81
	v_exp_f32_e32 v198, v81
	v_sub_f32_e32 v81, v148, v160
	v_mul_f32_e32 v81, 0x3fb8aa3b, v81
	v_exp_f32_e32 v199, v81
	v_sub_f32_e32 v81, v147, v160
	v_mul_f32_e32 v81, 0x3fb8aa3b, v81
	v_exp_f32_e32 v205, v81
	v_sub_f32_e32 v81, v146, v160
	v_mul_f32_e32 v81, 0x3fb8aa3b, v81
	v_exp_f32_e32 v206, v81
	v_sub_f32_e32 v81, v150, v160
	v_mul_f32_e32 v81, 0x3fb8aa3b, v81
	v_exp_f32_e32 v195, v81
	v_sub_f32_e32 v81, v151, v160
	v_mul_f32_e32 v81, 0x3fb8aa3b, v81
	v_exp_f32_e32 v196, v81
	v_sub_f32_e32 v81, v152, v160
	v_mul_f32_e32 v81, 0x3fb8aa3b, v81
	v_exp_f32_e32 v197, v81
	v_sub_f32_e32 v81, v153, v160
	v_mul_f32_e32 v81, 0x3fb8aa3b, v81
	v_exp_f32_e32 v202, v81
	v_sub_f32_e32 v81, v159, v160
	v_mul_f32_e32 v81, 0x3fb8aa3b, v81
	v_exp_f32_e32 v186, v81
	v_sub_f32_e32 v81, v156, v160
	v_mul_f32_e32 v81, 0x3fb8aa3b, v81
	v_exp_f32_e32 v187, v81
; DI f32x4 mfma16(s16x4 a, s16x4 b, f32x4 c) { return __builtin_amdgcn_mfma_f32_16x16x16bf16_1k(a, b, c, 0, 0, 0); }
; DI s16x4 pack4(f32x4 v) { uint2 w; w.x = pk(v[0], v[1]); w.y = pk(v[2], v[3]); return __builtin_bit_cast(s16x4, w); }
; DI void phase_na(const Ctx& c, LAS unsigned char* lds, int g, int l, const bf16* PROJ, bf16* MIX, int bid, int nb, int tid) {
;     ...
;         float sum = 0.f;
; #pragma unroll
;         for (int t = 0; t < 16; ++t)
; #pragma unroll
;             for (int j = 0; j < 4; ++j) { const float p = __expf(sc[t][j] - m); sc[t][j] = p; sum += p; }
;         sum += __shfl_xor(sum, 16); sum += __shfl_xor(sum, 32);
;         f32x4 o[4];
; #pragma unroll
;         for (int dt = 0; dt < 4; ++dt) o[dt] = (f32x4){0.f, 0.f, 0.f, 0.f};
; #pragma unroll
;         for (int t = 0; t < 16; ++t) { const int rr = t >> 1, hf = t & 1, krow = (r0 + rr - rbase) * 64 + kb0 + 16 * hf; const s16x4 pb = pack4(sc[t]);
; #pragma unroll
;             for (int dt = 0; dt < 4; ++dt) o[dt] = mfma16(ld_tr4(Vimg, 72, krow, dt * 16, lane), pb, o[dt]); }
	v_sub_f32_e32 v81, v155, v160
	v_mul_f32_e32 v81, 0x3fb8aa3b, v81
	v_exp_f32_e32 v189, v81
	v_sub_f32_e32 v81, v154, v160
	v_mul_f32_e32 v81, 0x3fb8aa3b, v81
	v_exp_f32_e32 v190, v81
	v_sub_f32_e32 v81, v164, v160
	v_mul_f32_e32 v81, 0x3fb8aa3b, v81
	v_exp_f32_e32 v183, v81
	v_sub_f32_e32 v81, v165, v160
	v_mul_f32_e32 v81, 0x3fb8aa3b, v81
	v_exp_f32_e32 v184, v81
	v_sub_f32_e32 v81, v166, v160
	v_mul_f32_e32 v81, 0x3fb8aa3b, v81
	v_exp_f32_e32 v185, v81
	v_sub_f32_e32 v81, v167, v160
	v_mul_f32_e32 v81, 0x3fb8aa3b, v81
	v_exp_f32_e32 v188, v81
	v_sub_f32_e32 v81, v171, v160
	v_mul_f32_e32 v81, 0x3fb8aa3b, v81
	v_exp_f32_e32 v171, v81
	v_sub_f32_e32 v81, v170, v160
	v_mul_f32_e32 v81, 0x3fb8aa3b, v81
	v_exp_f32_e32 v175, v81
	v_sub_f32_e32 v81, v169, v160
	v_mul_f32_e32 v81, 0x3fb8aa3b, v81
	v_exp_f32_e32 v177, v81
	v_sub_f32_e32 v81, v168, v160
	v_mul_f32_e32 v81, 0x3fb8aa3b, v81
	v_exp_f32_e32 v178, v81
	v_sub_f32_e32 v81, v172, v160
	v_mul_f32_e32 v81, 0x3fb8aa3b, v81
	v_exp_f32_e32 v168, v81
	v_sub_f32_e32 v81, v173, v160
	v_sub_f32_e32 v80, v141, v160
	v_mul_f32_e32 v81, 0x3fb8aa3b, v81
	v_mul_f32_e32 v80, 0x3fb8aa3b, v80
	v_exp_f32_e32 v169, v81
	v_sub_f32_e32 v81, v174, v160
	v_exp_f32_e32 v210, v80
	v_mul_f32_e32 v81, 0x3fb8aa3b, v81
	v_exp_f32_e32 v170, v81
	v_sub_f32_e32 v81, v176, v160
	v_mul_f32_e32 v81, 0x3fb8aa3b, v81
	v_exp_f32_e32 v172, v81
	v_sub_f32_e32 v81, v182, v160
	v_add_f32_e32 v80, 0, v210
	v_mul_f32_e32 v81, 0x3fb8aa3b, v81
	v_add_f32_e32 v80, v212, v80
	v_exp_f32_e32 v164, v81
	v_sub_f32_e32 v81, v181, v160
	v_add_f32_e32 v80, v218, v80
	v_mul_f32_e32 v81, 0x3fb8aa3b, v81
	v_add_f32_e32 v80, v221, v80
	v_exp_f32_e32 v165, v81
	v_sub_f32_e32 v81, v180, v160
	v_add_f32_e32 v80, v207, v80
	v_mul_f32_e32 v81, 0x3fb8aa3b, v81
	v_add_f32_e32 v80, v208, v80
	v_exp_f32_e32 v166, v81
	v_sub_f32_e32 v81, v179, v160
	v_add_f32_e32 v80, v209, v80
	v_mul_f32_e32 v81, 0x3fb8aa3b, v81
	v_add_f32_e32 v80, v211, v80
	v_exp_f32_e32 v167, v81
	v_sub_f32_e32 v81, v191, v160
	v_add_f32_e32 v80, v198, v80
	v_mul_f32_e32 v81, 0x3fb8aa3b, v81
	v_add_f32_e32 v80, v199, v80
	v_exp_f32_e32 v155, v81
	v_sub_f32_e32 v81, v192, v160
	v_add_f32_e32 v80, v205, v80
	v_mul_f32_e32 v81, 0x3fb8aa3b, v81
	v_add_f32_e32 v80, v206, v80
	v_exp_f32_e32 v156, v81
	v_sub_f32_e32 v81, v193, v160
	v_add_f32_e32 v80, v195, v80
	v_mul_f32_e32 v81, 0x3fb8aa3b, v81
	v_add_f32_e32 v80, v196, v80
	v_exp_f32_e32 v157, v81
	v_sub_f32_e32 v81, v194, v160
	v_add_f32_e32 v80, v197, v80
	v_mul_f32_e32 v81, 0x3fb8aa3b, v81
	v_add_f32_e32 v80, v202, v80
	v_exp_f32_e32 v159, v81
	v_sub_f32_e32 v81, v204, v160
	v_add_f32_e32 v80, v186, v80
	v_mul_f32_e32 v81, 0x3fb8aa3b, v81
	v_add_f32_e32 v80, v187, v80
	v_exp_f32_e32 v151, v81
	v_sub_f32_e32 v81, v203, v160
	v_add_f32_e32 v80, v189, v80
	v_mul_f32_e32 v81, 0x3fb8aa3b, v81
	v_add_f32_e32 v80, v190, v80
	v_exp_f32_e32 v152, v81
	v_sub_f32_e32 v81, v201, v160
	v_add_f32_e32 v80, v183, v80
	v_mul_f32_e32 v81, 0x3fb8aa3b, v81
	v_add_f32_e32 v80, v184, v80
	v_exp_f32_e32 v153, v81
	v_sub_f32_e32 v81, v200, v160
	v_add_f32_e32 v80, v185, v80
	v_mul_f32_e32 v81, 0x3fb8aa3b, v81
	v_add_f32_e32 v80, v188, v80
	v_exp_f32_e32 v154, v81
	v_sub_f32_e32 v81, v213, v160
	v_add_f32_e32 v80, v171, v80
	v_mul_f32_e32 v81, 0x3fb8aa3b, v81
	v_add_f32_e32 v80, v175, v80
	v_exp_f32_e32 v147, v81
	v_sub_f32_e32 v81, v219, v160
	v_add_f32_e32 v80, v177, v80
	v_mul_f32_e32 v81, 0x3fb8aa3b, v81
	v_add_f32_e32 v80, v178, v80
	v_exp_f32_e32 v148, v81
	v_sub_f32_e32 v81, v220, v160
	v_add_f32_e32 v80, v168, v80
	v_mul_f32_e32 v81, 0x3fb8aa3b, v81
	v_add_f32_e32 v80, v169, v80
	v_exp_f32_e32 v149, v81
	v_sub_f32_e32 v81, v222, v160
	v_add_f32_e32 v80, v170, v80
	v_mul_f32_e32 v81, 0x3fb8aa3b, v81
	v_add_f32_e32 v80, v172, v80
	v_exp_f32_e32 v150, v81
	v_sub_f32_e32 v81, v226, v160
	v_add_f32_e32 v80, v164, v80
	v_mul_f32_e32 v81, 0x3fb8aa3b, v81
	v_add_f32_e32 v80, v165, v80
	v_exp_f32_e32 v143, v81
	v_sub_f32_e32 v81, v225, v160
	v_add_f32_e32 v80, v166, v80
	v_mul_f32_e32 v81, 0x3fb8aa3b, v81
	v_add_f32_e32 v80, v167, v80
	v_exp_f32_e32 v144, v81
	v_sub_f32_e32 v81, v224, v160
	v_add_f32_e32 v80, v155, v80
	v_mul_f32_e32 v81, 0x3fb8aa3b, v81
	v_add_f32_e32 v80, v156, v80
	v_exp_f32_e32 v145, v81
	v_sub_f32_e32 v81, v223, v160
	v_add_f32_e32 v80, v157, v80
	v_mul_f32_e32 v81, 0x3fb8aa3b, v81
	v_add_f32_e32 v80, v159, v80
	v_exp_f32_e32 v146, v81
	v_sub_f32_e32 v81, v227, v160
	v_add_f32_e32 v80, v151, v80
	v_mul_f32_e32 v81, 0x3fb8aa3b, v81
	v_add_f32_e32 v80, v152, v80
	v_exp_f32_e32 v139, v81
	v_sub_f32_e32 v81, v228, v160
	v_add_f32_e32 v80, v153, v80
	v_mul_f32_e32 v81, 0x3fb8aa3b, v81
	v_add_f32_e32 v80, v154, v80
	v_exp_f32_e32 v140, v81
	v_sub_f32_e32 v81, v229, v160
	v_add_f32_e32 v80, v147, v80
	v_mul_f32_e32 v81, 0x3fb8aa3b, v81
	v_add_f32_e32 v80, v148, v80
	v_exp_f32_e32 v141, v81
	v_sub_f32_e32 v81, v230, v160
	v_add_f32_e32 v80, v149, v80
	v_mul_f32_e32 v81, 0x3fb8aa3b, v81
	v_add_f32_e32 v80, v150, v80
	v_exp_f32_e32 v142, v81
	v_sub_f32_e32 v81, v233, v160
	v_add_f32_e32 v80, v143, v80
	v_mul_f32_e32 v81, 0x3fb8aa3b, v81
	v_add_f32_e32 v80, v144, v80
	v_exp_f32_e32 v84, v81
	v_sub_f32_e32 v81, v232, v160
	v_add_f32_e32 v80, v145, v80
	v_mul_f32_e32 v81, 0x3fb8aa3b, v81
	v_add_f32_e32 v80, v146, v80
	v_exp_f32_e32 v85, v81
	v_sub_f32_e32 v81, v93, v160
	v_add_f32_e32 v80, v139, v80
	v_mul_f32_e32 v81, 0x3fb8aa3b, v81
	v_add_f32_e32 v80, v140, v80
	v_exp_f32_e32 v93, v81
	v_sub_f32_e32 v81, v231, v160
	v_add_f32_e32 v80, v141, v80
	v_mul_f32_e32 v81, 0x3fb8aa3b, v81
	v_add_f32_e32 v80, v142, v80
	v_exp_f32_e32 v138, v81
	v_add_f32_e32 v80, v84, v80
	v_add_f32_e32 v80, v85, v80
	v_sub_f32_e32 v78, v78, v160
	v_add_f32_e32 v80, v93, v80
	v_mul_f32_e32 v78, 0x3fb8aa3b, v78
	v_add_f32_e32 v81, v138, v80
	v_exp_f32_e32 v80, v78
	v_sub_f32_e32 v79, v79, v160
	v_mul_f32_e32 v79, 0x3fb8aa3b, v79
	v_cvt_pk_bf16_f32 v180, v210, v212
	v_add_f32_e32 v78, v80, v81
	v_exp_f32_e32 v81, v79
	v_sub_f32_e32 v79, v82, v160
	v_mul_f32_e32 v79, 0x3fb8aa3b, v79
	v_exp_f32_e32 v82, v79
	v_sub_f32_e32 v79, v83, v160
	v_add_u32_e32 v160, v91, v107
	v_mad_u64_u32 v[192:193], s[0:1], v160, s27, v[88:89]
	ds_read_b64_tr_b16 v[200:201], v192
	ds_read_b64_tr_b16 v[212:213], v192 offset:32
	v_cvt_pk_bf16_f32 v181, v218, v221
	v_add_u32_e32 v160, v91, v110
	v_cvt_pk_bf16_f32 v156, v155, v156
	s_waitcnt lgkmcnt(1)
; DI f32x4 mfma16(s16x4 a, s16x4 b, f32x4 c) { return __builtin_amdgcn_mfma_f32_16x16x16bf16_1k(a, b, c, 0, 0, 0); }
; DI s16x4 pack4(f32x4 v) { uint2 w; w.x = pk(v[0], v[1]); w.y = pk(v[2], v[3]); return __builtin_bit_cast(s16x4, w); }
; DI void phase_na(const Ctx& c, LAS unsigned char* lds, int g, int l, const bf16* PROJ, bf16* MIX, int bid, int nb, int tid) {
;     ...
;             for (int j = 0; j < 4; ++j) { const float p = __expf(sc[t][j] - m); sc[t][j] = p; sum += p; }
;         sum += __shfl_xor(sum, 16); sum += __shfl_xor(sum, 32);
;         f32x4 o[4];
; #pragma unroll
;         for (int dt = 0; dt < 4; ++dt) o[dt] = (f32x4){0.f, 0.f, 0.f, 0.f};
; #pragma unroll
;         for (int t = 0; t < 16; ++t) { const int rr = t >> 1, hf = t & 1, krow = (r0 + rr - rbase) * 64 + kb0 + 16 * hf; const s16x4 pb = pack4(sc[t]);
; #pragma unroll
;             for (int dt = 0; dt < 4; ++dt) o[dt] = mfma16(ld_tr4(Vimg, 72, krow, dt * 16, lane), pb, o[dt]); }
;         const float inv = 1.0f / sum;
	v_mfma_f32_16x16x16_bf16 v[218:221], v[200:201], v[180:181], 0
	ds_read_b64_tr_b16 v[200:201], v192 offset:64
	ds_read_b64_tr_b16 v[192:193], v192 offset:96
	v_cvt_pk_bf16_f32 v157, v157, v159
	s_waitcnt lgkmcnt(0)
	v_mfma_f32_16x16x16_bf16 v[230:233], v[192:193], v[180:181], 0
	v_mad_u64_u32 v[192:193], s[0:1], v160, s27, v[88:89]
	v_add_u32_e32 v160, 64, v91
	v_mfma_f32_16x16x16_bf16 v[222:225], v[212:213], v[180:181], 0
	v_add_u32_e32 v161, v160, v107
	v_add_u32_e32 v160, v160, v110
	v_add_u32_e32 v159, 0x140, v91
	v_mfma_f32_16x16x16_bf16 v[226:229], v[200:201], v[180:181], 0
	ds_read_b64_tr_b16 v[200:201], v192
	ds_read_b64_tr_b16 v[212:213], v192 offset:32
	v_cvt_pk_bf16_f32 v180, v207, v208
	v_cvt_pk_bf16_f32 v181, v209, v211
	v_cvt_pk_bf16_f32 v84, v84, v85
	v_cvt_pk_bf16_f32 v85, v93, v138
	s_waitcnt lgkmcnt(1)
	v_mfma_f32_16x16x16_bf16 v[208:211], v[200:201], v[180:181], v[218:221]
	ds_read_b64_tr_b16 v[200:201], v192 offset:64
	ds_read_b64_tr_b16 v[192:193], v192 offset:96
	v_mul_f32_e32 v79, 0x3fb8aa3b, v79
	s_waitcnt lgkmcnt(2)
	v_mfma_f32_16x16x16_bf16 v[218:221], v[212:213], v[180:181], v[222:225]
	v_mad_u64_u32 v[212:213], s[0:1], v160, s27, v[88:89]
	v_add_u32_e32 v160, 0x80, v91
	s_waitcnt lgkmcnt(1)
	v_mfma_f32_16x16x16_bf16 v[222:225], v[200:201], v[180:181], v[226:229]
	v_add_f32_e32 v78, v81, v78
	v_exp_f32_e32 v83, v79
	v_add_f32_e32 v78, v82, v78
	s_waitcnt lgkmcnt(0)
	v_mfma_f32_16x16x16_bf16 v[226:229], v[192:193], v[180:181], v[230:233]
	v_mad_u64_u32 v[192:193], s[0:1], v161, s27, v[88:89]
	v_cvt_pk_bf16_f32 v180, v198, v199
	v_cvt_pk_bf16_f32 v181, v205, v206
	ds_read_b64_tr_b16 v[198:199], v192
	ds_read_b64_tr_b16 v[204:205], v192 offset:32
	s_waitcnt lgkmcnt(1)
	v_mfma_f32_16x16x16_bf16 v[198:201], v[198:199], v[180:181], v[208:211]
	s_nop 2
	ds_read_b64_tr_b16 v[208:209], v192 offset:64
	ds_read_b64_tr_b16 v[192:193], v192 offset:96
	v_add_u32_e32 v161, v160, v107
	s_waitcnt lgkmcnt(2)
	v_mfma_f32_16x16x16_bf16 v[204:207], v[204:205], v[180:181], v[218:221]
	v_add_u32_e32 v160, v160, v110
	v_add_f32_e32 v78, v83, v78
	ds_bpermute_b32 v79, v105, v78
	s_waitcnt lgkmcnt(2)
	v_mfma_f32_16x16x16_bf16 v[208:211], v[208:209], v[180:181], v[222:225]
	s_waitcnt lgkmcnt(0)
	v_add_f32_e32 v78, v78, v79
	ds_bpermute_b32 v79, v106, v78
	v_mfma_f32_16x16x16_bf16 v[218:221], v[192:193], v[180:181], v[226:229]
	v_cvt_pk_bf16_f32 v180, v195, v196
	v_cvt_pk_bf16_f32 v181, v197, v202
	ds_read_b64_tr_b16 v[192:193], v212
	ds_read_b64_tr_b16 v[196:197], v212 offset:32
	s_waitcnt lgkmcnt(1)
	v_mfma_f32_16x16x16_bf16 v[192:195], v[192:193], v[180:181], v[198:201]
	s_nop 2
	ds_read_b64_tr_b16 v[200:201], v212 offset:64
	v_add_f32_e32 v78, v78, v79
	v_div_scale_f32 v79, s[0:1], v78, v78, 1.0
	s_waitcnt lgkmcnt(1)
	v_mfma_f32_16x16x16_bf16 v[196:199], v[196:197], v[180:181], v[204:207]
	s_nop 2
	ds_read_b64_tr_b16 v[204:205], v212 offset:96
	s_waitcnt lgkmcnt(1)
	v_mfma_f32_16x16x16_bf16 v[200:203], v[200:201], v[180:181], v[208:211]
	s_waitcnt lgkmcnt(0)
	v_mfma_f32_16x16x16_bf16 v[204:207], v[204:205], v[180:181], v[218:221]
	v_cvt_pk_bf16_f32 v180, v186, v187
	v_mad_u64_u32 v[186:187], s[0:1], v161, s27, v[88:89]
	v_cvt_pk_bf16_f32 v181, v189, v190
	ds_read_b64_tr_b16 v[190:191], v186
	ds_read_b64_tr_b16 v[208:209], v186 offset:32
	s_waitcnt lgkmcnt(1)
	v_mfma_f32_16x16x16_bf16 v[190:193], v[190:191], v[180:181], v[192:195]
	s_waitcnt lgkmcnt(0)
	v_mfma_f32_16x16x16_bf16 v[194:197], v[208:209], v[180:181], v[196:199]
	v_mad_u64_u32 v[208:209], s[0:1], v160, s27, v[88:89]
	v_add_u32_e32 v160, 0xc0, v91
	s_nop 0
	ds_read_b64_tr_b16 v[198:199], v186 offset:64
	ds_read_b64_tr_b16 v[186:187], v186 offset:96
	s_waitcnt lgkmcnt(1)
	v_mfma_f32_16x16x16_bf16 v[198:201], v[198:199], v[180:181], v[200:203]
	v_add_u32_e32 v161, v160, v107
	v_add_u32_e32 v160, v160, v110
	s_waitcnt lgkmcnt(0)
	v_mfma_f32_16x16x16_bf16 v[202:205], v[186:187], v[180:181], v[204:207]
	s_nop 2
	v_cvt_pk_bf16_f32 v206, v183, v184
	v_cvt_pk_bf16_f32 v207, v185, v188
	ds_read_b64_tr_b16 v[180:181], v208
	ds_read_b64_tr_b16 v[184:185], v208 offset:32
	ds_read_b64_tr_b16 v[188:189], v208 offset:64
	s_waitcnt lgkmcnt(2)
	v_mfma_f32_16x16x16_bf16 v[180:183], v[180:181], v[206:207], v[190:193]
	s_nop 2
	ds_read_b64_tr_b16 v[192:193], v208 offset:96
	s_waitcnt lgkmcnt(1)
	v_mfma_f32_16x16x16_bf16 v[188:191], v[188:189], v[206:207], v[198:201]
	s_nop 2
	v_mad_u64_u32 v[198:199], s[0:1], v161, s27, v[88:89]
	v_mfma_f32_16x16x16_bf16 v[184:187], v[184:185], v[206:207], v[194:197]
	s_nop 2
	v_cvt_pk_bf16_f32 v196, v171, v175
	v_cvt_pk_bf16_f32 v197, v177, v178
	ds_read_b64_tr_b16 v[174:175], v198
	ds_read_b64_tr_b16 v[178:179], v198 offset:32
	s_waitcnt lgkmcnt(1)
	v_mfma_f32_16x16x16_bf16 v[174:177], v[174:175], v[196:197], v[180:183]
	s_nop 2
	ds_read_b64_tr_b16 v[182:183], v198 offset:64
	s_waitcnt lgkmcnt(1)
	v_mfma_f32_16x16x16_bf16 v[178:181], v[178:179], v[196:197], v[184:187]
	s_nop 2
	ds_read_b64_tr_b16 v[186:187], v198 offset:96
	v_mfma_f32_16x16x16_bf16 v[192:195], v[192:193], v[206:207], v[202:205]
	s_waitcnt lgkmcnt(1)
	v_mfma_f32_16x16x16_bf16 v[182:185], v[182:183], v[196:197], v[188:191]
	s_waitcnt lgkmcnt(0)
	v_mfma_f32_16x16x16_bf16 v[186:189], v[186:187], v[196:197], v[192:195]
	s_nop 0
	v_cvt_pk_bf16_f32 v190, v168, v169
	v_cvt_pk_bf16_f32 v191, v170, v172
	s_nop 0
	v_mad_u64_u32 v[192:193], s[0:1], v160, s27, v[88:89]
	ds_read_b64_tr_b16 v[168:169], v192
	ds_read_b64_tr_b16 v[172:173], v192 offset:32
	s_waitcnt lgkmcnt(1)
	v_mfma_f32_16x16x16_bf16 v[168:171], v[168:169], v[190:191], v[174:177]
	s_nop 2
	ds_read_b64_tr_b16 v[176:177], v192 offset:64
	v_add_u32_e32 v160, 0x100, v91
	v_add_u32_e32 v161, v160, v107
	s_waitcnt lgkmcnt(1)
; DI f32x4 mfma16(s16x4 a, s16x4 b, f32x4 c) { return __builtin_amdgcn_mfma_f32_16x16x16bf16_1k(a, b, c, 0, 0, 0); }
; DI s16x4 pack4(f32x4 v) { uint2 w; w.x = pk(v[0], v[1]); w.y = pk(v[2], v[3]); return __builtin_bit_cast(s16x4, w); }
; DI void phase_na(const Ctx& c, LAS unsigned char* lds, int g, int l, const bf16* PROJ, bf16* MIX, int bid, int nb, int tid) {
;     ...
;         for (int t = 0; t < 16; ++t) { const int rr = t >> 1, hf = t & 1, krow = (r0 + rr - rbase) * 64 + kb0 + 16 * hf; const s16x4 pb = pack4(sc[t]);
; #pragma unroll
;             for (int dt = 0; dt < 4; ++dt) o[dt] = mfma16(ld_tr4(Vimg, 72, krow, dt * 16, lane), pb, o[dt]); }
	v_mfma_f32_16x16x16_bf16 v[172:175], v[172:173], v[190:191], v[178:181]
	v_add_u32_e32 v155, v160, v110
	s_nop 1
	ds_read_b64_tr_b16 v[180:181], v192 offset:96
	s_waitcnt lgkmcnt(1)
	v_mfma_f32_16x16x16_bf16 v[176:179], v[176:177], v[190:191], v[182:185]
	s_nop 2
	v_cvt_pk_bf16_f32 v184, v164, v165
	s_waitcnt lgkmcnt(0)
	v_mfma_f32_16x16x16_bf16 v[180:183], v[180:181], v[190:191], v[186:189]
	s_nop 2
	v_mad_u64_u32 v[186:187], s[0:1], v161, s27, v[88:89]
	ds_read_b64_tr_b16 v[164:165], v186
	ds_read_b64_tr_b16 v[188:189], v186 offset:32
	v_cvt_pk_bf16_f32 v185, v166, v167
	s_waitcnt lgkmcnt(1)
	s_nop 0
	v_mfma_f32_16x16x16_bf16 v[164:167], v[164:165], v[184:185], v[168:171]
	s_waitcnt lgkmcnt(0)
	v_mfma_f32_16x16x16_bf16 v[168:171], v[188:189], v[184:185], v[172:175]
	s_nop 2
	ds_read_b64_tr_b16 v[172:173], v186 offset:64
	s_waitcnt lgkmcnt(0)
	v_mfma_f32_16x16x16_bf16 v[172:175], v[172:173], v[184:185], v[176:179]
	s_nop 2
	ds_read_b64_tr_b16 v[176:177], v186 offset:96
	s_waitcnt lgkmcnt(0)
	v_mfma_f32_16x16x16_bf16 v[176:179], v[176:177], v[184:185], v[180:183]
	s_nop 2
	v_mad_u64_u32 v[180:181], s[0:1], v155, s27, v[88:89]
	ds_read_b64_tr_b16 v[182:183], v180
	ds_read_b64_tr_b16 v[184:185], v180 offset:32
	s_waitcnt lgkmcnt(1)
	v_mfma_f32_16x16x16_bf16 v[164:167], v[182:183], v[156:157], v[164:167]
	ds_read_b64_tr_b16 v[182:183], v180 offset:64
	ds_read_b64_tr_b16 v[180:181], v180 offset:96
	s_waitcnt lgkmcnt(2)
	v_mfma_f32_16x16x16_bf16 v[168:171], v[184:185], v[156:157], v[168:171]
	s_waitcnt lgkmcnt(1)
	v_mfma_f32_16x16x16_bf16 v[172:175], v[182:183], v[156:157], v[172:175]
	s_waitcnt lgkmcnt(0)
	v_mfma_f32_16x16x16_bf16 v[176:179], v[180:181], v[156:157], v[176:179]
	v_cvt_pk_bf16_f32 v156, v151, v152
	v_add_u32_e32 v151, v159, v107
	v_mad_u64_u32 v[180:181], s[0:1], v151, s27, v[88:89]
	v_cvt_pk_bf16_f32 v157, v153, v154
	ds_read_b64_tr_b16 v[152:153], v180
	ds_read_b64_tr_b16 v[182:183], v180 offset:32
	s_waitcnt lgkmcnt(1)
	v_mfma_f32_16x16x16_bf16 v[152:155], v[152:153], v[156:157], v[164:167]
	s_waitcnt lgkmcnt(0)
	v_mfma_f32_16x16x16_bf16 v[164:167], v[182:183], v[156:157], v[168:171]
	s_nop 2
	ds_read_b64_tr_b16 v[168:169], v180 offset:64
	s_waitcnt lgkmcnt(0)
	v_mfma_f32_16x16x16_bf16 v[168:171], v[168:169], v[156:157], v[172:175]
	s_nop 2
	ds_read_b64_tr_b16 v[172:173], v180 offset:96
	s_waitcnt lgkmcnt(0)
	v_mfma_f32_16x16x16_bf16 v[172:175], v[172:173], v[156:157], v[176:179]
	v_cvt_pk_bf16_f32 v156, v147, v148
	v_add_u32_e32 v147, v159, v110
	s_nop 0
	v_mad_u64_u32 v[176:177], s[0:1], v147, s27, v[88:89]
	v_cvt_pk_bf16_f32 v157, v149, v150
	ds_read_b64_tr_b16 v[148:149], v176
	ds_read_b64_tr_b16 v[178:179], v176 offset:32
	s_waitcnt lgkmcnt(1)
	v_mfma_f32_16x16x16_bf16 v[148:151], v[148:149], v[156:157], v[152:155]
	v_add_u32_e32 v159, 0x180, v91
	v_add_u32_e32 v91, 0x1c0, v91
	v_add_u32_e32 v93, v91, v107
	s_waitcnt lgkmcnt(0)
	v_mfma_f32_16x16x16_bf16 v[152:155], v[178:179], v[156:157], v[164:167]
	s_nop 2
	ds_read_b64_tr_b16 v[164:165], v176 offset:64
	s_waitcnt lgkmcnt(0)
	v_mfma_f32_16x16x16_bf16 v[164:167], v[164:165], v[156:157], v[168:171]
	s_nop 2
	ds_read_b64_tr_b16 v[168:169], v176 offset:96
	s_waitcnt lgkmcnt(0)
	v_mfma_f32_16x16x16_bf16 v[168:171], v[168:169], v[156:157], v[172:175]
	v_cvt_pk_bf16_f32 v156, v143, v144
	v_add_u32_e32 v143, v159, v107
	s_nop 0
	v_mad_u64_u32 v[172:173], s[0:1], v143, s27, v[88:89]
	v_cvt_pk_bf16_f32 v157, v145, v146
	ds_read_b64_tr_b16 v[144:145], v172
	ds_read_b64_tr_b16 v[174:175], v172 offset:32
	s_waitcnt lgkmcnt(1)
	v_mfma_f32_16x16x16_bf16 v[144:147], v[144:145], v[156:157], v[148:151]
	s_waitcnt lgkmcnt(0)
	v_mfma_f32_16x16x16_bf16 v[148:151], v[174:175], v[156:157], v[152:155]
	s_nop 2
	ds_read_b64_tr_b16 v[152:153], v172 offset:64
	s_waitcnt lgkmcnt(0)
	v_mfma_f32_16x16x16_bf16 v[152:155], v[152:153], v[156:157], v[164:167]
	s_nop 2
	ds_read_b64_tr_b16 v[164:165], v172 offset:96
	s_waitcnt lgkmcnt(0)
; DI unsigned pk(float lo, float hi) { return pg8::cvt_pk_bf16(lo, hi); }
; DI f32x4 mfma16(s16x4 a, s16x4 b, f32x4 c) { return __builtin_amdgcn_mfma_f32_16x16x16bf16_1k(a, b, c, 0, 0, 0); }
; DI s16x4 pack4(f32x4 v) { uint2 w; w.x = pk(v[0], v[1]); w.y = pk(v[2], v[3]); return __builtin_bit_cast(s16x4, w); }
; DI void phase_na(const Ctx& c, LAS unsigned char* lds, int g, int l, const bf16* PROJ, bf16* MIX, int bid, int nb, int tid) {
;     ...
;         for (int t = 0; t < 16; ++t) { const int rr = t >> 1, hf = t & 1, krow = (r0 + rr - rbase) * 64 + kb0 + 16 * hf; const s16x4 pb = pack4(sc[t]);
; #pragma unroll
;             for (int dt = 0; dt < 4; ++dt) o[dt] = mfma16(ld_tr4(Vimg, 72, krow, dt * 16, lane), pb, o[dt]); }
;         const float inv = 1.0f / sum;
; #pragma unroll
;         for (int dt = 0; dt < 4; ++dt) { uint2 wv; wv.x = pk(o[dt][0] * inv, o[dt][1] * inv); wv.y = pk(o[dt][2] * inv, o[dt][3] * inv);
;             *(uint2*)(MIX + (size_t)qtok * DM + h * 64 + dt * 16 + gq * 4) = wv; }
;         __syncthreads();
	v_mfma_f32_16x16x16_bf16 v[164:167], v[164:165], v[156:157], v[168:171]
	v_cvt_pk_bf16_f32 v156, v139, v140
	v_add_u32_e32 v139, v159, v110
	s_nop 0
	v_mad_u64_u32 v[168:169], s[0:1], v139, s27, v[88:89]
	v_cvt_pk_bf16_f32 v157, v141, v142
	ds_read_b64_tr_b16 v[140:141], v168
	ds_read_b64_tr_b16 v[170:171], v168 offset:32
	s_waitcnt lgkmcnt(1)
	v_mfma_f32_16x16x16_bf16 v[140:143], v[140:141], v[156:157], v[144:147]
	s_waitcnt lgkmcnt(0)
	v_mfma_f32_16x16x16_bf16 v[144:147], v[170:171], v[156:157], v[148:151]
	s_nop 2
	ds_read_b64_tr_b16 v[148:149], v168 offset:64
	s_waitcnt lgkmcnt(0)
	v_mfma_f32_16x16x16_bf16 v[148:151], v[148:149], v[156:157], v[152:155]
	s_nop 2
	ds_read_b64_tr_b16 v[152:153], v168 offset:96
	s_waitcnt lgkmcnt(0)
	v_mfma_f32_16x16x16_bf16 v[152:155], v[152:153], v[156:157], v[164:167]
	v_mad_u64_u32 v[156:157], s[0:1], v93, s27, v[88:89]
	ds_read_b64_tr_b16 v[138:139], v156
	s_nop 0
	ds_read_b64_tr_b16 v[164:165], v156 offset:32
	s_waitcnt lgkmcnt(1)
	v_mfma_f32_16x16x16_bf16 v[138:141], v[138:139], v[84:85], v[140:143]
	s_waitcnt lgkmcnt(0)
	v_mfma_f32_16x16x16_bf16 v[142:145], v[164:165], v[84:85], v[144:147]
	s_nop 2
	ds_read_b64_tr_b16 v[146:147], v156 offset:64
	s_waitcnt lgkmcnt(0)
	v_mfma_f32_16x16x16_bf16 v[146:149], v[146:147], v[84:85], v[148:151]
	s_nop 2
	ds_read_b64_tr_b16 v[150:151], v156 offset:96
	s_waitcnt lgkmcnt(0)
	v_mfma_f32_16x16x16_bf16 v[150:153], v[150:151], v[84:85], v[152:155]
	v_cvt_pk_bf16_f32 v84, v80, v81
	v_add_u32_e32 v80, v91, v110
	s_nop 0
	v_mad_u64_u32 v[154:155], s[0:1], v80, s27, v[88:89]
	ds_read_b64_tr_b16 v[80:81], v154
	ds_read_b64_tr_b16 v[156:157], v154 offset:32
	v_cvt_pk_bf16_f32 v85, v82, v83
	v_readlane_b32 s0, v252, 22
	v_readlane_b32 s1, v252, 23
	s_waitcnt lgkmcnt(1)
	v_mfma_f32_16x16x16_bf16 v[80:83], v[80:81], v[84:85], v[138:141]
	s_waitcnt lgkmcnt(0)
	v_mfma_f32_16x16x16_bf16 v[138:141], v[156:157], v[84:85], v[142:145]
	s_nop 2
	ds_read_b64_tr_b16 v[142:143], v154 offset:64
	s_waitcnt lgkmcnt(0)
	v_mfma_f32_16x16x16_bf16 v[142:145], v[142:143], v[84:85], v[146:149]
	s_nop 2
	ds_read_b64_tr_b16 v[146:147], v154 offset:96
	s_waitcnt lgkmcnt(0)
	v_mfma_f32_16x16x16_bf16 v[146:149], v[146:147], v[84:85], v[150:153]
	v_rcp_f32_e32 v84, v79
	s_nop 0
	v_fma_f32 v85, -v79, v84, 1.0
	v_fmac_f32_e32 v84, v85, v84
	v_div_scale_f32 v85, vcc, 1.0, v78, 1.0
	v_mul_f32_e32 v91, v85, v84
	v_fma_f32 v93, -v79, v91, v85
	v_fmac_f32_e32 v91, v93, v84
	v_fma_f32 v79, -v79, v91, v85
	v_div_fmas_f32 v79, v79, v84, v91
	v_lshlrev_b64 v[84:85], 11, v[94:95]
	v_div_fixup_f32 v78, v79, v78, 1.0
	v_lshl_add_u64 v[84:85], s[0:1], 0, v[84:85]
	v_lshl_add_u64 v[84:85], s[6:7], 1, v[84:85]
	v_mov_b32_e32 v93, v0
	v_pk_mul_f32 v[80:81], v[78:79], v[80:81] op_sel_hi:[0,1]
	v_pk_mul_f32 v[82:83], v[78:79], v[82:83] op_sel_hi:[0,1]
	v_lshl_add_u64 v[84:85], v[84:85], 0, v[92:93]
	v_cvt_pk_bf16_f32 v80, v80, v81
	v_cvt_pk_bf16_f32 v81, v82, v83
	global_store_dwordx2 v[84:85], v[80:81], off
	v_pk_mul_f32 v[80:81], v[78:79], v[138:139] op_sel_hi:[0,1]
	v_pk_mul_f32 v[82:83], v[78:79], v[140:141] op_sel_hi:[0,1]
	v_cvt_pk_bf16_f32 v80, v80, v81
	v_cvt_pk_bf16_f32 v81, v82, v83
	global_store_dwordx2 v[84:85], v[80:81], off offset:32
	v_pk_mul_f32 v[80:81], v[78:79], v[142:143] op_sel_hi:[0,1]
	v_pk_mul_f32 v[82:83], v[78:79], v[144:145] op_sel_hi:[0,1]
	v_cvt_pk_bf16_f32 v80, v80, v81
	v_cvt_pk_bf16_f32 v81, v82, v83
	global_store_dwordx2 v[84:85], v[80:81], off offset:64
	v_pk_mul_f32 v[80:81], v[78:79], v[146:147] op_sel_hi:[0,1]
	v_pk_mul_f32 v[78:79], v[78:79], v[148:149] op_sel_hi:[0,1]
	v_cvt_pk_bf16_f32 v80, v80, v81
	v_cvt_pk_bf16_f32 v81, v78, v79
	s_andn2_b64 vcc, exec, s[8:9]
	s_mov_b32 s0, s10
	global_store_dwordx2 v[84:85], v[80:81], off offset:96
	s_barrier
	s_cbranch_vccz .LBB0_218
